# seam polling with two staggered loads in flight on the cross-XCC counter
# baseline (speedup 1.0000x reference)
; __device__ __forceinline__ unsigned xb_ld(unsigned* p)              { return __hip_atomic_load(p, __ATOMIC_RELAXED, __HIP_MEMORY_SCOPE_AGENT); }
; #define XB_SPIN(cond, bar) do { unsigned _sp = 0; while (cond) { __builtin_amdgcn_s_sleep(1); \
;     if ((++_sp & 255u) == 0u) { if (xb_ld(&(bar)[XB_TMO])) break; if (_sp > XB_SPIN_CAP) { atomicAdd(&(bar)[XB_TMO], 1u); break; } } } } while (0)
; __device__ __forceinline__ void xcd_barrier(const XcdBarrier& b) {
;     ...
;             else XB_SPIN(xb_ld(&bar[XB_TOPGEN]) == tg, bar);
.Lxb_poll_s0:
	global_load_dword v253, v2, s[100:101] sc1
	s_sleep 5
	global_load_dword v254, v2, s[100:101] sc1
.Lxb_loop_s0:
	s_waitcnt vmcnt(1)
	v_cmp_ge_u32_e32 vcc, v253, v1
	s_cbranch_vccnz .Lxb_done_s0
	global_load_dword v253, v2, s[100:101] sc1
	s_waitcnt vmcnt(1)
	v_cmp_ge_u32_e32 vcc, v254, v1
	s_cbranch_vccnz .Lxb_done_s0
	global_load_dword v254, v2, s[100:101] sc1
	s_branch .Lxb_loop_s0
